# out-proj EpiRes epilogue rewritten: 2-deep base prefetch, saddr addressing, cvt_pk packing; plus down-last prefetch and EpiUp rowsq hoist
# speedup vs baseline: 1.0021x; 1.0021x over previous
.LBB0_1065:
	s_lshl_b32 s15, s26, 8
	s_add_i32 s17, s15, 0xffff8000
	s_and_b64 s[22:23], s[22:23], exec
	s_cselect_b32 s17, s15, s17
	s_cselect_b32 s23, s35, s56
	s_cselect_b32 s22, s53, s94
	v_readlane_b32 s100, v253, 59
	v_add_u32_e32 v188, s17, v196
	s_cselect_b32 s25, s75, s100
	v_readlane_b32 s100, v253, 58
	v_add_u32_e32 v182, s15, v196
	s_cselect_b32 s24, s74, s100
	v_readlane_b32 s26, v254, 49
	v_readlane_b32 s27, v254, 50
	v_lshl_add_u32 v190, v188, 10, v168
	v_lshl_add_u32 v191, v182, 10, v168
	v_lshlrev_b32_e32 v192, 2, v182
	v_lshlrev_b32_e32 v190, 2, v190
	v_lshlrev_b32_e32 v191, 1, v191
	global_load_dwordx4 v[208:211], v190, s[22:23]
	global_load_dwordx4 v[212:215], v190, s[22:23] offset:16
	global_load_dwordx4 v[216:219], v190, s[22:23] offset:512
	global_load_dwordx4 v[220:223], v190, s[22:23] offset:528
	s_add_u32 s22, s22, 0x10000
	s_addc_u32 s23, s23, 0
	global_load_dwordx4 v[154:157], v190, s[22:23]
	global_load_dwordx4 v[158:161], v190, s[22:23] offset:16
	global_load_dwordx4 v[162:165], v190, s[22:23] offset:512
	global_load_dwordx4 v[224:227], v190, s[22:23] offset:528
	s_add_u32 s22, s22, 0x10000
	s_addc_u32 s23, s23, 0
	s_waitcnt vmcnt(4)
	v_pk_fma_f32 v[140:141], v[140:141], v[72:73], v[208:209]
	v_pk_fma_f32 v[142:143], v[142:143], v[74:75], v[210:211]
	v_pk_fma_f32 v[136:137], v[136:137], v[80:81], v[212:213]
	v_pk_fma_f32 v[138:139], v[138:139], v[82:83], v[214:215]
	v_pk_fma_f32 v[132:133], v[132:133], v[64:65], v[216:217]
	v_pk_fma_f32 v[134:135], v[134:135], v[66:67], v[218:219]
	v_pk_fma_f32 v[128:129], v[128:129], v[68:69], v[220:221]
	v_pk_fma_f32 v[130:131], v[130:131], v[70:71], v[222:223]
	global_store_dwordx4 v190, v[140:143], s[24:25]
	global_store_dwordx4 v190, v[136:139], s[24:25] offset:16
	global_store_dwordx4 v190, v[132:135], s[24:25] offset:512
	global_store_dwordx4 v190, v[128:131], s[24:25] offset:528
	s_add_u32 s24, s24, 0x10000
	s_addc_u32 s25, s25, 0
	v_pk_mul_f32 v[200:201], v[140:141], v[140:141]
	v_pk_fma_f32 v[200:201], v[142:143], v[142:143], v[200:201]
	v_pk_fma_f32 v[200:201], v[136:137], v[136:137], v[200:201]
	v_pk_fma_f32 v[200:201], v[138:139], v[138:139], v[200:201]
	v_pk_fma_f32 v[200:201], v[132:133], v[132:133], v[200:201]
	v_pk_fma_f32 v[200:201], v[134:135], v[134:135], v[200:201]
	v_pk_fma_f32 v[200:201], v[128:129], v[128:129], v[200:201]
	v_pk_fma_f32 v[200:201], v[130:131], v[130:131], v[200:201]
	v_add_f32_e32 v193, v200, v201
	ds_bpermute_b32 v194, v206, v193
	v_pk_mul_f32 v[140:141], v[174:175], v[140:141]
	v_pk_mul_f32 v[142:143], v[176:177], v[142:143]
	v_pk_mul_f32 v[136:137], v[184:185], v[136:137]
	v_pk_mul_f32 v[138:139], v[186:187], v[138:139]
	v_pk_mul_f32 v[132:133], v[170:171], v[132:133]
	v_pk_mul_f32 v[134:135], v[172:173], v[134:135]
	v_pk_mul_f32 v[128:129], v[178:179], v[128:129]
	v_pk_mul_f32 v[130:131], v[180:181], v[130:131]
	v_cvt_pk_bf16_f32 v140, v140, v141
	v_cvt_pk_bf16_f32 v141, v142, v143
	v_cvt_pk_bf16_f32 v142, v136, v137
	v_cvt_pk_bf16_f32 v143, v138, v139
	v_cvt_pk_bf16_f32 v132, v132, v133
	v_cvt_pk_bf16_f32 v133, v134, v135
	v_cvt_pk_bf16_f32 v134, v128, v129
	v_cvt_pk_bf16_f32 v135, v130, v131
	global_store_dwordx4 v191, v[140:143], s[26:27]
	global_store_dwordx4 v191, v[132:135], s[26:27] offset:256
	s_add_u32 s26, s26, 0x8000
	s_addc_u32 s27, s27, 0
	s_waitcnt lgkmcnt(0)
	v_add_f32_e32 v193, v193, v194
	ds_bpermute_b32 v194, v207, v193
	s_waitcnt lgkmcnt(0)
	v_add_f32_e32 v193, v193, v194
	s_and_saveexec_b64 s[100:101], s[2:3]
	s_cbranch_execz .Lepi_op_na0
	global_atomic_add_f32 v192, v193, s[54:55]
.Lepi_op_na0:
	s_or_b64 exec, exec, s[100:101]
	global_load_dwordx4 v[140:143], v190, s[22:23]
	global_load_dwordx4 v[136:139], v190, s[22:23] offset:16
	global_load_dwordx4 v[132:135], v190, s[22:23] offset:512
	global_load_dwordx4 v[128:131], v190, s[22:23] offset:528
	s_add_u32 s22, s22, 0x10000
	s_addc_u32 s23, s23, 0
	s_waitcnt vmcnt(10)
	v_pk_fma_f32 v[124:125], v[124:125], v[72:73], v[154:155]
	v_pk_fma_f32 v[126:127], v[126:127], v[74:75], v[156:157]
	v_pk_fma_f32 v[120:121], v[120:121], v[80:81], v[158:159]
	v_pk_fma_f32 v[122:123], v[122:123], v[82:83], v[160:161]
	v_pk_fma_f32 v[116:117], v[116:117], v[64:65], v[162:163]
	v_pk_fma_f32 v[118:119], v[118:119], v[66:67], v[164:165]
	v_pk_fma_f32 v[112:113], v[112:113], v[68:69], v[224:225]
	v_pk_fma_f32 v[114:115], v[114:115], v[70:71], v[226:227]
	global_store_dwordx4 v190, v[124:127], s[24:25]
	global_store_dwordx4 v190, v[120:123], s[24:25] offset:16
	global_store_dwordx4 v190, v[116:119], s[24:25] offset:512
	global_store_dwordx4 v190, v[112:115], s[24:25] offset:528
	s_add_u32 s24, s24, 0x10000
	s_addc_u32 s25, s25, 0
	v_pk_mul_f32 v[200:201], v[124:125], v[124:125]
	v_pk_fma_f32 v[200:201], v[126:127], v[126:127], v[200:201]
	v_pk_fma_f32 v[200:201], v[120:121], v[120:121], v[200:201]
	v_pk_fma_f32 v[200:201], v[122:123], v[122:123], v[200:201]
	v_pk_fma_f32 v[200:201], v[116:117], v[116:117], v[200:201]
	v_pk_fma_f32 v[200:201], v[118:119], v[118:119], v[200:201]
	v_pk_fma_f32 v[200:201], v[112:113], v[112:113], v[200:201]
	v_pk_fma_f32 v[200:201], v[114:115], v[114:115], v[200:201]
	v_add_f32_e32 v193, v200, v201
	ds_bpermute_b32 v194, v206, v193
	v_pk_mul_f32 v[124:125], v[174:175], v[124:125]
	v_pk_mul_f32 v[126:127], v[176:177], v[126:127]
	v_pk_mul_f32 v[120:121], v[184:185], v[120:121]
	v_pk_mul_f32 v[122:123], v[186:187], v[122:123]
	v_pk_mul_f32 v[116:117], v[170:171], v[116:117]
	v_pk_mul_f32 v[118:119], v[172:173], v[118:119]
	v_pk_mul_f32 v[112:113], v[178:179], v[112:113]
	v_pk_mul_f32 v[114:115], v[180:181], v[114:115]
	v_cvt_pk_bf16_f32 v124, v124, v125
	v_cvt_pk_bf16_f32 v125, v126, v127
	v_cvt_pk_bf16_f32 v126, v120, v121
	v_cvt_pk_bf16_f32 v127, v122, v123
	v_cvt_pk_bf16_f32 v116, v116, v117
	v_cvt_pk_bf16_f32 v117, v118, v119
	v_cvt_pk_bf16_f32 v118, v112, v113
	v_cvt_pk_bf16_f32 v119, v114, v115
	global_store_dwordx4 v191, v[124:127], s[26:27]
	global_store_dwordx4 v191, v[116:119], s[26:27] offset:256
	s_add_u32 s26, s26, 0x8000
	s_addc_u32 s27, s27, 0
	s_waitcnt lgkmcnt(0)
	v_add_f32_e32 v193, v193, v194
	ds_bpermute_b32 v194, v207, v193
	s_waitcnt lgkmcnt(0)
	v_add_f32_e32 v193, v193, v194
	s_and_saveexec_b64 s[100:101], s[2:3]
	s_cbranch_execz .Lepi_op_na1
	global_atomic_add_f32 v192, v193, s[54:55] offset:64
.Lepi_op_na1:
	s_or_b64 exec, exec, s[100:101]
	global_load_dwordx4 v[124:127], v190, s[22:23]
	global_load_dwordx4 v[120:123], v190, s[22:23] offset:16
	global_load_dwordx4 v[116:119], v190, s[22:23] offset:512
	global_load_dwordx4 v[112:115], v190, s[22:23] offset:528
	s_add_u32 s22, s22, 0x50000
	s_addc_u32 s23, s23, 0
	s_waitcnt vmcnt(10)
	v_pk_fma_f32 v[108:109], v[108:109], v[72:73], v[140:141]
	v_pk_fma_f32 v[110:111], v[110:111], v[74:75], v[142:143]
	v_pk_fma_f32 v[104:105], v[104:105], v[80:81], v[136:137]
	v_pk_fma_f32 v[106:107], v[106:107], v[82:83], v[138:139]
	v_pk_fma_f32 v[100:101], v[100:101], v[64:65], v[132:133]
	v_pk_fma_f32 v[102:103], v[102:103], v[66:67], v[134:135]
	v_pk_fma_f32 v[96:97], v[96:97], v[68:69], v[128:129]
	v_pk_fma_f32 v[98:99], v[98:99], v[70:71], v[130:131]
	global_store_dwordx4 v190, v[108:111], s[24:25]
	global_store_dwordx4 v190, v[104:107], s[24:25] offset:16
	global_store_dwordx4 v190, v[100:103], s[24:25] offset:512
	global_store_dwordx4 v190, v[96:99], s[24:25] offset:528
	s_add_u32 s24, s24, 0x10000
	s_addc_u32 s25, s25, 0
	v_pk_mul_f32 v[200:201], v[108:109], v[108:109]
	v_pk_fma_f32 v[200:201], v[110:111], v[110:111], v[200:201]
	v_pk_fma_f32 v[200:201], v[104:105], v[104:105], v[200:201]
	v_pk_fma_f32 v[200:201], v[106:107], v[106:107], v[200:201]
	v_pk_fma_f32 v[200:201], v[100:101], v[100:101], v[200:201]
	v_pk_fma_f32 v[200:201], v[102:103], v[102:103], v[200:201]
	v_pk_fma_f32 v[200:201], v[96:97], v[96:97], v[200:201]
	v_pk_fma_f32 v[200:201], v[98:99], v[98:99], v[200:201]
	v_add_f32_e32 v193, v200, v201
	ds_bpermute_b32 v194, v206, v193
	v_pk_mul_f32 v[108:109], v[174:175], v[108:109]
	v_pk_mul_f32 v[110:111], v[176:177], v[110:111]
	v_pk_mul_f32 v[104:105], v[184:185], v[104:105]
	v_pk_mul_f32 v[106:107], v[186:187], v[106:107]
	v_pk_mul_f32 v[100:101], v[170:171], v[100:101]
	v_pk_mul_f32 v[102:103], v[172:173], v[102:103]
	v_pk_mul_f32 v[96:97], v[178:179], v[96:97]
	v_pk_mul_f32 v[98:99], v[180:181], v[98:99]
	v_cvt_pk_bf16_f32 v108, v108, v109
	v_cvt_pk_bf16_f32 v109, v110, v111
	v_cvt_pk_bf16_f32 v110, v104, v105
	v_cvt_pk_bf16_f32 v111, v106, v107
	v_cvt_pk_bf16_f32 v100, v100, v101
	v_cvt_pk_bf16_f32 v101, v102, v103
	v_cvt_pk_bf16_f32 v102, v96, v97
	v_cvt_pk_bf16_f32 v103, v98, v99
	global_store_dwordx4 v191, v[108:111], s[26:27]
	global_store_dwordx4 v191, v[100:103], s[26:27] offset:256
	s_add_u32 s26, s26, 0x8000
	s_addc_u32 s27, s27, 0
	s_waitcnt lgkmcnt(0)
	v_add_f32_e32 v193, v193, v194
	ds_bpermute_b32 v194, v207, v193
	s_waitcnt lgkmcnt(0)
	v_add_f32_e32 v193, v193, v194
	s_and_saveexec_b64 s[100:101], s[2:3]
	s_cbranch_execz .Lepi_op_na2
	global_atomic_add_f32 v192, v193, s[54:55] offset:128
.Lepi_op_na2:
	s_or_b64 exec, exec, s[100:101]
	global_load_dwordx4 v[108:111], v190, s[22:23]
	global_load_dwordx4 v[104:107], v190, s[22:23] offset:16
	global_load_dwordx4 v[100:103], v190, s[22:23] offset:512
	global_load_dwordx4 v[96:99], v190, s[22:23] offset:528
	s_add_u32 s22, s22, 0x10000
	s_addc_u32 s23, s23, 0
	s_waitcnt vmcnt(10)
	v_pk_fma_f32 v[92:93], v[92:93], v[72:73], v[124:125]
	v_pk_fma_f32 v[94:95], v[94:95], v[74:75], v[126:127]
	v_pk_fma_f32 v[88:89], v[88:89], v[80:81], v[120:121]
	v_pk_fma_f32 v[90:91], v[90:91], v[82:83], v[122:123]
	v_pk_fma_f32 v[84:85], v[84:85], v[64:65], v[116:117]
	v_pk_fma_f32 v[86:87], v[86:87], v[66:67], v[118:119]
	v_pk_fma_f32 v[76:77], v[76:77], v[68:69], v[112:113]
	v_pk_fma_f32 v[78:79], v[78:79], v[70:71], v[114:115]
	global_store_dwordx4 v190, v[92:95], s[24:25]
	global_store_dwordx4 v190, v[88:91], s[24:25] offset:16
	global_store_dwordx4 v190, v[84:87], s[24:25] offset:512
	global_store_dwordx4 v190, v[76:79], s[24:25] offset:528
	s_add_u32 s24, s24, 0x50000
	s_addc_u32 s25, s25, 0
	v_pk_mul_f32 v[200:201], v[92:93], v[92:93]
	v_pk_fma_f32 v[200:201], v[94:95], v[94:95], v[200:201]
	v_pk_fma_f32 v[200:201], v[88:89], v[88:89], v[200:201]
	v_pk_fma_f32 v[200:201], v[90:91], v[90:91], v[200:201]
	v_pk_fma_f32 v[200:201], v[84:85], v[84:85], v[200:201]
	v_pk_fma_f32 v[200:201], v[86:87], v[86:87], v[200:201]
	v_pk_fma_f32 v[200:201], v[76:77], v[76:77], v[200:201]
	v_pk_fma_f32 v[200:201], v[78:79], v[78:79], v[200:201]
	v_add_f32_e32 v193, v200, v201
	ds_bpermute_b32 v194, v206, v193
	v_pk_mul_f32 v[92:93], v[174:175], v[92:93]
	v_pk_mul_f32 v[94:95], v[176:177], v[94:95]
	v_pk_mul_f32 v[88:89], v[184:185], v[88:89]
	v_pk_mul_f32 v[90:91], v[186:187], v[90:91]
	v_pk_mul_f32 v[84:85], v[170:171], v[84:85]
	v_pk_mul_f32 v[86:87], v[172:173], v[86:87]
	v_pk_mul_f32 v[76:77], v[178:179], v[76:77]
	v_pk_mul_f32 v[78:79], v[180:181], v[78:79]
	v_cvt_pk_bf16_f32 v92, v92, v93
	v_cvt_pk_bf16_f32 v93, v94, v95
	v_cvt_pk_bf16_f32 v94, v88, v89
	v_cvt_pk_bf16_f32 v95, v90, v91
	v_cvt_pk_bf16_f32 v84, v84, v85
	v_cvt_pk_bf16_f32 v85, v86, v87
	v_cvt_pk_bf16_f32 v86, v76, v77
	v_cvt_pk_bf16_f32 v87, v78, v79
	global_store_dwordx4 v191, v[92:95], s[26:27]
	global_store_dwordx4 v191, v[84:87], s[26:27] offset:256
	s_add_u32 s26, s26, 0x28000
	s_addc_u32 s27, s27, 0
	s_waitcnt lgkmcnt(0)
	v_add_f32_e32 v193, v193, v194
	ds_bpermute_b32 v194, v207, v193
	s_waitcnt lgkmcnt(0)
	v_add_f32_e32 v193, v193, v194
	s_and_saveexec_b64 s[100:101], s[2:3]
	s_cbranch_execz .Lepi_op_na3
	global_atomic_add_f32 v192, v193, s[54:55] offset:192
.Lepi_op_na3:
	s_or_b64 exec, exec, s[100:101]
	global_load_dwordx4 v[92:95], v190, s[22:23]
	global_load_dwordx4 v[88:91], v190, s[22:23] offset:16
	global_load_dwordx4 v[84:87], v190, s[22:23] offset:512
	global_load_dwordx4 v[76:79], v190, s[22:23] offset:528
	s_add_u32 s22, s22, 0x10000
	s_addc_u32 s23, s23, 0
	s_waitcnt vmcnt(10)
	v_pk_fma_f32 v[60:61], v[60:61], v[72:73], v[108:109]
	v_pk_fma_f32 v[62:63], v[62:63], v[74:75], v[110:111]
	v_pk_fma_f32 v[56:57], v[56:57], v[80:81], v[104:105]
	v_pk_fma_f32 v[58:59], v[58:59], v[82:83], v[106:107]
	v_pk_fma_f32 v[52:53], v[52:53], v[64:65], v[100:101]
	v_pk_fma_f32 v[54:55], v[54:55], v[66:67], v[102:103]
	v_pk_fma_f32 v[48:49], v[48:49], v[68:69], v[96:97]
	v_pk_fma_f32 v[50:51], v[50:51], v[70:71], v[98:99]
	global_store_dwordx4 v190, v[60:63], s[24:25]
	global_store_dwordx4 v190, v[56:59], s[24:25] offset:16
	global_store_dwordx4 v190, v[52:55], s[24:25] offset:512
	global_store_dwordx4 v190, v[48:51], s[24:25] offset:528
	s_add_u32 s24, s24, 0x10000
	s_addc_u32 s25, s25, 0
	v_pk_mul_f32 v[200:201], v[60:61], v[60:61]
	v_pk_fma_f32 v[200:201], v[62:63], v[62:63], v[200:201]
	v_pk_fma_f32 v[200:201], v[56:57], v[56:57], v[200:201]
	v_pk_fma_f32 v[200:201], v[58:59], v[58:59], v[200:201]
	v_pk_fma_f32 v[200:201], v[52:53], v[52:53], v[200:201]
	v_pk_fma_f32 v[200:201], v[54:55], v[54:55], v[200:201]
	v_pk_fma_f32 v[200:201], v[48:49], v[48:49], v[200:201]
	v_pk_fma_f32 v[200:201], v[50:51], v[50:51], v[200:201]
	v_add_f32_e32 v193, v200, v201
	ds_bpermute_b32 v194, v206, v193
	v_pk_mul_f32 v[60:61], v[174:175], v[60:61]
	v_pk_mul_f32 v[62:63], v[176:177], v[62:63]
	v_pk_mul_f32 v[56:57], v[184:185], v[56:57]
	v_pk_mul_f32 v[58:59], v[186:187], v[58:59]
	v_pk_mul_f32 v[52:53], v[170:171], v[52:53]
	v_pk_mul_f32 v[54:55], v[172:173], v[54:55]
	v_pk_mul_f32 v[48:49], v[178:179], v[48:49]
	v_pk_mul_f32 v[50:51], v[180:181], v[50:51]
	v_cvt_pk_bf16_f32 v60, v60, v61
	v_cvt_pk_bf16_f32 v61, v62, v63
	v_cvt_pk_bf16_f32 v62, v56, v57
	v_cvt_pk_bf16_f32 v63, v58, v59
	v_cvt_pk_bf16_f32 v52, v52, v53
	v_cvt_pk_bf16_f32 v53, v54, v55
	v_cvt_pk_bf16_f32 v54, v48, v49
	v_cvt_pk_bf16_f32 v55, v50, v51
	global_store_dwordx4 v191, v[60:63], s[26:27]
	global_store_dwordx4 v191, v[52:55], s[26:27] offset:256
	s_add_u32 s26, s26, 0x8000
	s_addc_u32 s27, s27, 0
	s_waitcnt lgkmcnt(0)
	v_add_f32_e32 v193, v193, v194
	ds_bpermute_b32 v194, v207, v193
	s_waitcnt lgkmcnt(0)
	v_add_f32_e32 v193, v193, v194
	s_and_saveexec_b64 s[100:101], s[2:3]
	s_cbranch_execz .Lepi_op_na4
	global_atomic_add_f32 v192, v193, s[54:55] offset:512
.Lepi_op_na4:
	s_or_b64 exec, exec, s[100:101]
	global_load_dwordx4 v[60:63], v190, s[22:23]
	global_load_dwordx4 v[56:59], v190, s[22:23] offset:16
	global_load_dwordx4 v[52:55], v190, s[22:23] offset:512
	global_load_dwordx4 v[48:51], v190, s[22:23] offset:528
	s_add_u32 s22, s22, 0x10000
	s_addc_u32 s23, s23, 0
	s_waitcnt vmcnt(10)
	v_pk_fma_f32 v[44:45], v[44:45], v[72:73], v[92:93]
	v_pk_fma_f32 v[46:47], v[46:47], v[74:75], v[94:95]
	v_pk_fma_f32 v[40:41], v[40:41], v[80:81], v[88:89]
	v_pk_fma_f32 v[42:43], v[42:43], v[82:83], v[90:91]
	v_pk_fma_f32 v[36:37], v[36:37], v[64:65], v[84:85]
	v_pk_fma_f32 v[38:39], v[38:39], v[66:67], v[86:87]
	v_pk_fma_f32 v[32:33], v[32:33], v[68:69], v[76:77]
	v_pk_fma_f32 v[34:35], v[34:35], v[70:71], v[78:79]
	global_store_dwordx4 v190, v[44:47], s[24:25]
	global_store_dwordx4 v190, v[40:43], s[24:25] offset:16
	global_store_dwordx4 v190, v[36:39], s[24:25] offset:512
	global_store_dwordx4 v190, v[32:35], s[24:25] offset:528
	s_add_u32 s24, s24, 0x10000
	s_addc_u32 s25, s25, 0
	v_pk_mul_f32 v[200:201], v[44:45], v[44:45]
	v_pk_fma_f32 v[200:201], v[46:47], v[46:47], v[200:201]
	v_pk_fma_f32 v[200:201], v[40:41], v[40:41], v[200:201]
	v_pk_fma_f32 v[200:201], v[42:43], v[42:43], v[200:201]
	v_pk_fma_f32 v[200:201], v[36:37], v[36:37], v[200:201]
	v_pk_fma_f32 v[200:201], v[38:39], v[38:39], v[200:201]
	v_pk_fma_f32 v[200:201], v[32:33], v[32:33], v[200:201]
	v_pk_fma_f32 v[200:201], v[34:35], v[34:35], v[200:201]
	v_add_f32_e32 v193, v200, v201
	ds_bpermute_b32 v194, v206, v193
	v_pk_mul_f32 v[44:45], v[174:175], v[44:45]
	v_pk_mul_f32 v[46:47], v[176:177], v[46:47]
	v_pk_mul_f32 v[40:41], v[184:185], v[40:41]
	v_pk_mul_f32 v[42:43], v[186:187], v[42:43]
	v_pk_mul_f32 v[36:37], v[170:171], v[36:37]
	v_pk_mul_f32 v[38:39], v[172:173], v[38:39]
	v_pk_mul_f32 v[32:33], v[178:179], v[32:33]
	v_pk_mul_f32 v[34:35], v[180:181], v[34:35]
	v_cvt_pk_bf16_f32 v44, v44, v45
	v_cvt_pk_bf16_f32 v45, v46, v47
	v_cvt_pk_bf16_f32 v46, v40, v41
	v_cvt_pk_bf16_f32 v47, v42, v43
	v_cvt_pk_bf16_f32 v36, v36, v37
	v_cvt_pk_bf16_f32 v37, v38, v39
	v_cvt_pk_bf16_f32 v38, v32, v33
	v_cvt_pk_bf16_f32 v39, v34, v35
	global_store_dwordx4 v191, v[44:47], s[26:27]
	global_store_dwordx4 v191, v[36:39], s[26:27] offset:256
	s_add_u32 s26, s26, 0x8000
	s_addc_u32 s27, s27, 0
	s_waitcnt lgkmcnt(0)
	v_add_f32_e32 v193, v193, v194
	ds_bpermute_b32 v194, v207, v193
	s_waitcnt lgkmcnt(0)
	v_add_f32_e32 v193, v193, v194
	s_and_saveexec_b64 s[100:101], s[2:3]
	s_cbranch_execz .Lepi_op_na5
	global_atomic_add_f32 v192, v193, s[54:55] offset:576
.Lepi_op_na5:
	s_or_b64 exec, exec, s[100:101]
	global_load_dwordx4 v[44:47], v190, s[22:23]
	global_load_dwordx4 v[40:43], v190, s[22:23] offset:16
	global_load_dwordx4 v[36:39], v190, s[22:23] offset:512
	global_load_dwordx4 v[32:35], v190, s[22:23] offset:528
	s_waitcnt vmcnt(10)
	v_pk_fma_f32 v[28:29], v[28:29], v[72:73], v[60:61]
	v_pk_fma_f32 v[30:31], v[30:31], v[74:75], v[62:63]
	v_pk_fma_f32 v[24:25], v[24:25], v[80:81], v[56:57]
	v_pk_fma_f32 v[26:27], v[26:27], v[82:83], v[58:59]
	v_pk_fma_f32 v[20:21], v[20:21], v[64:65], v[52:53]
	v_pk_fma_f32 v[22:23], v[22:23], v[66:67], v[54:55]
	v_pk_fma_f32 v[16:17], v[16:17], v[68:69], v[48:49]
	v_pk_fma_f32 v[18:19], v[18:19], v[70:71], v[50:51]
	global_store_dwordx4 v190, v[28:31], s[24:25]
	global_store_dwordx4 v190, v[24:27], s[24:25] offset:16
	global_store_dwordx4 v190, v[20:23], s[24:25] offset:512
	global_store_dwordx4 v190, v[16:19], s[24:25] offset:528
	s_add_u32 s24, s24, 0x10000
	s_addc_u32 s25, s25, 0
	v_pk_mul_f32 v[200:201], v[28:29], v[28:29]
	v_pk_fma_f32 v[200:201], v[30:31], v[30:31], v[200:201]
	v_pk_fma_f32 v[200:201], v[24:25], v[24:25], v[200:201]
	v_pk_fma_f32 v[200:201], v[26:27], v[26:27], v[200:201]
	v_pk_fma_f32 v[200:201], v[20:21], v[20:21], v[200:201]
	v_pk_fma_f32 v[200:201], v[22:23], v[22:23], v[200:201]
	v_pk_fma_f32 v[200:201], v[16:17], v[16:17], v[200:201]
	v_pk_fma_f32 v[200:201], v[18:19], v[18:19], v[200:201]
	v_add_f32_e32 v193, v200, v201
	ds_bpermute_b32 v194, v206, v193
	v_pk_mul_f32 v[28:29], v[174:175], v[28:29]
	v_pk_mul_f32 v[30:31], v[176:177], v[30:31]
	v_pk_mul_f32 v[24:25], v[184:185], v[24:25]
	v_pk_mul_f32 v[26:27], v[186:187], v[26:27]
	v_pk_mul_f32 v[20:21], v[170:171], v[20:21]
	v_pk_mul_f32 v[22:23], v[172:173], v[22:23]
	v_pk_mul_f32 v[16:17], v[178:179], v[16:17]
	v_pk_mul_f32 v[18:19], v[180:181], v[18:19]
	v_cvt_pk_bf16_f32 v28, v28, v29
	v_cvt_pk_bf16_f32 v29, v30, v31
	v_cvt_pk_bf16_f32 v30, v24, v25
	v_cvt_pk_bf16_f32 v31, v26, v27
	v_cvt_pk_bf16_f32 v20, v20, v21
	v_cvt_pk_bf16_f32 v21, v22, v23
	v_cvt_pk_bf16_f32 v22, v16, v17
	v_cvt_pk_bf16_f32 v23, v18, v19
	global_store_dwordx4 v191, v[28:31], s[26:27]
	global_store_dwordx4 v191, v[20:23], s[26:27] offset:256
	s_add_u32 s26, s26, 0x8000
	s_addc_u32 s27, s27, 0
	s_waitcnt lgkmcnt(0)
	v_add_f32_e32 v193, v193, v194
	ds_bpermute_b32 v194, v207, v193
	s_waitcnt lgkmcnt(0)
	v_add_f32_e32 v193, v193, v194
	s_and_saveexec_b64 s[100:101], s[2:3]
	s_cbranch_execz .Lepi_op_na6
	global_atomic_add_f32 v192, v193, s[54:55] offset:640
.Lepi_op_na6:
	s_or_b64 exec, exec, s[100:101]
	s_waitcnt vmcnt(6)
	v_pk_fma_f32 v[12:13], v[12:13], v[72:73], v[44:45]
	v_pk_fma_f32 v[14:15], v[14:15], v[74:75], v[46:47]
	v_pk_fma_f32 v[8:9], v[8:9], v[80:81], v[40:41]
	v_pk_fma_f32 v[10:11], v[10:11], v[82:83], v[42:43]
	v_pk_fma_f32 v[4:5], v[4:5], v[64:65], v[36:37]
	v_pk_fma_f32 v[6:7], v[6:7], v[66:67], v[38:39]
	v_pk_fma_f32 v[0:1], v[0:1], v[68:69], v[32:33]
	v_pk_fma_f32 v[2:3], v[2:3], v[70:71], v[34:35]
	global_store_dwordx4 v190, v[12:15], s[24:25]
	global_store_dwordx4 v190, v[8:11], s[24:25] offset:16
	global_store_dwordx4 v190, v[4:7], s[24:25] offset:512
	global_store_dwordx4 v190, v[0:3], s[24:25] offset:528
	v_pk_mul_f32 v[200:201], v[12:13], v[12:13]
	v_pk_fma_f32 v[200:201], v[14:15], v[14:15], v[200:201]
	v_pk_fma_f32 v[200:201], v[8:9], v[8:9], v[200:201]
	v_pk_fma_f32 v[200:201], v[10:11], v[10:11], v[200:201]
	v_pk_fma_f32 v[200:201], v[4:5], v[4:5], v[200:201]
	v_pk_fma_f32 v[200:201], v[6:7], v[6:7], v[200:201]
	v_pk_fma_f32 v[200:201], v[0:1], v[0:1], v[200:201]
	v_pk_fma_f32 v[200:201], v[2:3], v[2:3], v[200:201]
	v_add_f32_e32 v193, v200, v201
	ds_bpermute_b32 v194, v206, v193
	v_pk_mul_f32 v[12:13], v[174:175], v[12:13]
	v_pk_mul_f32 v[14:15], v[176:177], v[14:15]
	v_pk_mul_f32 v[8:9], v[184:185], v[8:9]
	v_pk_mul_f32 v[10:11], v[186:187], v[10:11]
	v_pk_mul_f32 v[4:5], v[170:171], v[4:5]
	v_pk_mul_f32 v[6:7], v[172:173], v[6:7]
	v_pk_mul_f32 v[0:1], v[178:179], v[0:1]
	v_pk_mul_f32 v[2:3], v[180:181], v[2:3]
	v_cvt_pk_bf16_f32 v12, v12, v13
	v_cvt_pk_bf16_f32 v13, v14, v15
	v_cvt_pk_bf16_f32 v14, v8, v9
	v_cvt_pk_bf16_f32 v15, v10, v11
	v_cvt_pk_bf16_f32 v4, v4, v5
	v_cvt_pk_bf16_f32 v5, v6, v7
	v_cvt_pk_bf16_f32 v6, v0, v1
	v_cvt_pk_bf16_f32 v7, v2, v3
	global_store_dwordx4 v191, v[12:15], s[26:27]
	global_store_dwordx4 v191, v[4:7], s[26:27] offset:256
	s_waitcnt lgkmcnt(0)
	v_add_f32_e32 v193, v193, v194
	ds_bpermute_b32 v194, v207, v193
	s_waitcnt lgkmcnt(0)
	v_add_f32_e32 v193, v193, v194
	s_and_saveexec_b64 s[100:101], s[2:3]
	s_cbranch_execz .Lepi_op_na7
	global_atomic_add_f32 v192, v193, s[54:55] offset:704
.Lepi_op_na7:
	s_or_b64 exec, exec, s[100:101]

.LBB0_1179:
	s_ashr_i32 s18, s56, 3
	v_lshl_add_u32 v172, s56, 8, v176
	s_ashr_i32 s19, s18, 31
	v_ashrrev_i32_e32 v173, 31, v172
	s_lshl_b64 s[18:19], s[18:19], 12
	v_lshl_add_u64 v[170:171], v[172:173], 2, s[54:55]
	s_cmpk_lt_i32 s56, 0x80
	global_load_dword v158, v[170:171], off
	global_load_dword v184, v[170:171], off offset:64
	global_load_dword v185, v[170:171], off offset:128
	global_load_dword v186, v[170:171], off offset:192
	global_load_dword v187, v[170:171], off offset:512
	global_load_dword v188, v[170:171], off offset:576
	global_load_dword v189, v[170:171], off offset:640
	global_load_dword v190, v[170:171], off offset:704
	s_cselect_b32 s19, s19, 0
	s_cselect_b32 s18, s18, 0x10000
	s_lshl_b64 s[18:19], s[18:19], 2
	v_lshl_or_b32 v154, s89, 8, v178
	s_add_u32 s18, s35, s18
	s_addc_u32 s19, s50, s19
	v_ashrrev_i32_e32 v155, 31, v154
	v_lshl_add_u64 v[72:73], v[154:155], 2, s[18:19]
	global_load_dwordx4 v[84:87], v[72:73], off
	global_load_dwordx4 v[80:83], v[72:73], off offset:16
	global_load_dwordx4 v[76:79], v[72:73], off offset:512
	s_nop 0
	global_load_dwordx4 v[72:75], v[72:73], off offset:528
	v_lshlrev_b64 v[156:157], 13, v[172:173]
	v_lshlrev_b64 v[174:175], 1, v[154:155]
	v_lshl_add_u64 v[154:155], s[70:71], 0, v[156:157]
	v_lshl_add_u64 v[168:169], v[154:155], 0, v[174:175]
	s_mov_b32 s11, 0x100000
	s_mov_b64 s[18:19], 0x100000
	v_readlane_b32 s94, v255, 32
	v_readlane_b32 s95, v255, 33
	s_waitcnt vmcnt(0)
	v_fmamk_f32 v158, v158, 0x3a800000, v228
	v_rsq_f32_e32 v158, v158
	s_nop 0
	v_pk_fma_f32 v[142:143], v[142:143], v[158:159], v[86:87] op_sel_hi:[1,0,1]
	v_pk_fma_f32 v[140:141], v[140:141], v[158:159], v[84:85] op_sel_hi:[1,0,1]
	v_pk_fma_f32 v[138:139], v[138:139], v[158:159], v[82:83] op_sel_hi:[1,0,1]
	v_pk_fma_f32 v[136:137], v[136:137], v[158:159], v[80:81] op_sel_hi:[1,0,1]
	v_pk_fma_f32 v[130:131], v[130:131], v[158:159], v[74:75] op_sel_hi:[1,0,1]
	v_pk_fma_f32 v[128:129], v[128:129], v[158:159], v[72:73] op_sel_hi:[1,0,1]
	v_max_f32_e32 v140, 0, v140
	v_max_f32_e32 v136, 0, v136
	v_max_f32_e32 v154, 0, v141
	v_max_f32_e32 v156, 0, v137
	v_max_f32_e32 v141, 0, v142
	v_max_f32_e32 v137, 0, v138
	v_pk_fma_f32 v[134:135], v[134:135], v[158:159], v[78:79] op_sel_hi:[1,0,1]
	v_pk_fma_f32 v[132:133], v[132:133], v[158:159], v[76:77] op_sel_hi:[1,0,1]
	v_max_f32_e32 v155, 0, v143
	v_max_f32_e32 v157, 0, v139
	v_max_f32_e32 v128, 0, v128
	v_max_f32_e32 v142, 0, v129
	v_max_f32_e32 v129, 0, v130
	v_max_f32_e32 v143, 0, v131
	v_pk_mul_f32 v[130:131], v[140:141], v[140:141]
	v_pk_mul_f32 v[136:137], v[136:137], v[136:137]
	v_max_f32_e32 v138, 0, v133
	v_max_f32_e32 v133, 0, v134
	v_max_f32_e32 v139, 0, v135
	v_pk_mul_f32 v[134:135], v[154:155], v[154:155]
	v_pk_mul_f32 v[140:141], v[156:157], v[156:157]
	v_pk_mul_f32 v[128:129], v[128:129], v[128:129]
	v_bfe_u32 v158, v130, 16, 1
	v_bfe_u32 v159, v131, 16, 1
	v_bfe_u32 v160, v136, 16, 1
	v_bfe_u32 v161, v137, 16, 1
	v_max_f32_e32 v132, 0, v132
	v_bfe_u32 v154, v141, 16, 1
	v_bfe_u32 v155, v140, 16, 1
	v_bfe_u32 v156, v135, 16, 1
	v_bfe_u32 v157, v134, 16, 1
	v_bfe_u32 v181, v128, 16, 1
	v_bfe_u32 v182, v129, 16, 1
	v_add3_u32 v137, v137, v161, s96
	v_add3_u32 v136, v136, v160, s96
	v_add3_u32 v131, v131, v159, s96
	v_add3_u32 v130, v130, v158, s96
	v_pk_mul_f32 v[132:133], v[132:133], v[132:133]
	v_add3_u32 v134, v134, v157, s96
	v_add3_u32 v135, v135, v156, s96
	v_add3_u32 v140, v140, v155, s96
	v_add3_u32 v141, v141, v154, s96
	v_add3_u32 v154, v129, v182, s96
	v_add3_u32 v155, v128, v181, s96
	v_lshrrev_b32_e32 v128, 16, v130
	v_lshrrev_b32_e32 v129, 16, v131
	v_lshrrev_b32_e32 v130, 16, v136
	v_lshrrev_b32_e32 v131, 16, v137
	v_pk_mul_f32 v[138:139], v[138:139], v[138:139]
	v_pk_mul_f32 v[142:143], v[142:143], v[142:143]
	v_bfe_u32 v173, v132, 16, 1
	v_bfe_u32 v180, v133, 16, 1
	v_and_or_b32 v131, v141, s97, v131
	v_and_or_b32 v130, v140, s97, v130
	v_and_or_b32 v129, v135, s97, v129
	v_and_or_b32 v128, v134, s97, v128
	v_bfe_u32 v162, v143, 16, 1
	v_bfe_u32 v163, v142, 16, 1
	v_bfe_u32 v164, v139, 16, 1
	v_bfe_u32 v165, v138, 16, 1
	global_store_dwordx4 v[168:169], v[128:131], off
	v_add3_u32 v138, v138, v165, s96
	v_add3_u32 v139, v139, v164, s96
	v_add3_u32 v128, v133, v180, s96
	v_add3_u32 v129, v132, v173, s96
	v_add3_u32 v142, v142, v163, s96
	v_add3_u32 v143, v143, v162, s96
	v_lshrrev_b32_e32 v132, 16, v129
	v_lshrrev_b32_e32 v128, 16, v128
	v_lshrrev_b32_e32 v129, 16, v155
	v_lshrrev_b32_e32 v130, 16, v154
	v_and_or_b32 v131, v143, s97, v130
	v_and_or_b32 v130, v142, s97, v129
	v_and_or_b32 v129, v139, s97, v128
	v_and_or_b32 v128, v138, s97, v132
	global_store_dwordx4 v[168:169], v[128:131], off offset:256
	s_nop 0
	s_nop 0
	v_or_b32_e32 v128, 16, v172
	v_ashrrev_i32_e32 v129, 31, v128
	v_lshlrev_b64 v[128:129], 13, v[128:129]
	v_lshl_add_u64 v[128:129], s[70:71], 0, v[128:129]
	v_lshl_add_u64 v[128:129], v[128:129], 0, v[174:175]
	s_nop 0
	v_fmamk_f32 v130, v184, 0x3a800000, v228
	v_rsq_f32_e32 v130, v130
	s_nop 0
	v_pk_fma_f32 v[126:127], v[126:127], v[130:131], v[86:87] op_sel_hi:[1,0,1]
	v_pk_fma_f32 v[124:125], v[124:125], v[130:131], v[84:85] op_sel_hi:[1,0,1]
	v_pk_fma_f32 v[122:123], v[122:123], v[130:131], v[82:83] op_sel_hi:[1,0,1]
	v_pk_fma_f32 v[120:121], v[120:121], v[130:131], v[80:81] op_sel_hi:[1,0,1]
	v_pk_fma_f32 v[118:119], v[118:119], v[130:131], v[78:79] op_sel_hi:[1,0,1]
	v_pk_fma_f32 v[116:117], v[116:117], v[130:131], v[76:77] op_sel_hi:[1,0,1]
	v_pk_fma_f32 v[114:115], v[114:115], v[130:131], v[74:75] op_sel_hi:[1,0,1]
	v_pk_fma_f32 v[112:113], v[112:113], v[130:131], v[72:73] op_sel_hi:[1,0,1]
	v_max_f32_e32 v124, 0, v124
	v_max_f32_e32 v120, 0, v120
	v_max_f32_e32 v130, 0, v125
	v_max_f32_e32 v132, 0, v121
	v_max_f32_e32 v125, 0, v126
	v_max_f32_e32 v121, 0, v122
	v_max_f32_e32 v131, 0, v127
	v_max_f32_e32 v133, 0, v123
	v_max_f32_e32 v116, 0, v116
	v_max_f32_e32 v112, 0, v112
	v_max_f32_e32 v122, 0, v117
	v_max_f32_e32 v126, 0, v113
	v_max_f32_e32 v117, 0, v118
	v_max_f32_e32 v113, 0, v114
	v_max_f32_e32 v127, 0, v115
	v_pk_mul_f32 v[114:115], v[124:125], v[124:125]
	v_pk_mul_f32 v[120:121], v[120:121], v[120:121]
	v_max_f32_e32 v123, 0, v119
	v_pk_mul_f32 v[118:119], v[130:131], v[130:131]
	v_pk_mul_f32 v[124:125], v[132:133], v[132:133]
	v_pk_mul_f32 v[116:117], v[116:117], v[116:117]
	v_pk_mul_f32 v[112:113], v[112:113], v[112:113]
	v_bfe_u32 v134, v114, 16, 1
	v_bfe_u32 v135, v115, 16, 1
	v_bfe_u32 v136, v120, 16, 1
	v_bfe_u32 v137, v121, 16, 1
	v_bfe_u32 v130, v125, 16, 1
	v_bfe_u32 v131, v124, 16, 1
	v_bfe_u32 v132, v119, 16, 1
	v_bfe_u32 v133, v118, 16, 1
	v_bfe_u32 v142, v116, 16, 1
	v_bfe_u32 v154, v112, 16, 1
	v_bfe_u32 v155, v113, 16, 1
	v_add3_u32 v121, v121, v137, s96
	v_add3_u32 v120, v120, v136, s96
	v_add3_u32 v115, v115, v135, s96
	v_add3_u32 v114, v114, v134, s96
	v_pk_mul_f32 v[122:123], v[122:123], v[122:123]
	v_pk_mul_f32 v[126:127], v[126:127], v[126:127]
	v_bfe_u32 v143, v117, 16, 1
	v_add3_u32 v118, v118, v133, s96
	v_add3_u32 v119, v119, v132, s96
	v_add3_u32 v124, v124, v131, s96
	v_add3_u32 v125, v125, v130, s96
	v_add3_u32 v130, v113, v155, s96
	v_add3_u32 v131, v112, v154, s96
	v_add3_u32 v112, v116, v142, s96
	v_lshrrev_b32_e32 v116, 16, v114
	v_lshrrev_b32_e32 v113, 16, v115
	v_lshrrev_b32_e32 v114, 16, v120
	v_lshrrev_b32_e32 v115, 16, v121
	v_bfe_u32 v138, v127, 16, 1
	v_bfe_u32 v139, v126, 16, 1
	v_bfe_u32 v140, v123, 16, 1
	v_bfe_u32 v141, v122, 16, 1
	v_add3_u32 v117, v117, v143, s96
	v_lshrrev_b32_e32 v120, 16, v112
	v_and_or_b32 v115, v125, s97, v115
	v_and_or_b32 v114, v124, s97, v114
	v_and_or_b32 v113, v119, s97, v113
	v_and_or_b32 v112, v118, s97, v116
	v_add3_u32 v122, v122, v141, s96
	v_add3_u32 v123, v123, v140, s96
	v_add3_u32 v126, v126, v139, s96
	v_add3_u32 v127, v127, v138, s96
	global_store_dwordx4 v[128:129], v[112:115], off
	s_nop 1
	v_lshrrev_b32_e32 v112, 16, v117
	v_lshrrev_b32_e32 v113, 16, v131
	v_lshrrev_b32_e32 v114, 16, v130
	v_and_or_b32 v115, v127, s97, v114
	v_and_or_b32 v114, v126, s97, v113
	v_and_or_b32 v113, v123, s97, v112
	v_and_or_b32 v112, v122, s97, v120
	global_store_dwordx4 v[128:129], v[112:115], off offset:256
	s_nop 0
	s_nop 0
	v_or_b32_e32 v112, 32, v172
	v_ashrrev_i32_e32 v113, 31, v112
	v_lshlrev_b64 v[112:113], 13, v[112:113]
	v_lshl_add_u64 v[112:113], s[70:71], 0, v[112:113]
	v_lshl_add_u64 v[112:113], v[112:113], 0, v[174:175]
	s_nop 0
	v_fmamk_f32 v114, v185, 0x3a800000, v228
	v_rsq_f32_e32 v114, v114
	s_nop 0
	v_pk_fma_f32 v[110:111], v[110:111], v[114:115], v[86:87] op_sel_hi:[1,0,1]
	v_pk_fma_f32 v[108:109], v[108:109], v[114:115], v[84:85] op_sel_hi:[1,0,1]
	v_pk_fma_f32 v[106:107], v[106:107], v[114:115], v[82:83] op_sel_hi:[1,0,1]
	v_pk_fma_f32 v[104:105], v[104:105], v[114:115], v[80:81] op_sel_hi:[1,0,1]
	v_pk_fma_f32 v[102:103], v[102:103], v[114:115], v[78:79] op_sel_hi:[1,0,1]
	v_pk_fma_f32 v[100:101], v[100:101], v[114:115], v[76:77] op_sel_hi:[1,0,1]
	v_pk_fma_f32 v[98:99], v[98:99], v[114:115], v[74:75] op_sel_hi:[1,0,1]
	v_pk_fma_f32 v[96:97], v[96:97], v[114:115], v[72:73] op_sel_hi:[1,0,1]
	v_max_f32_e32 v108, 0, v108
	v_max_f32_e32 v104, 0, v104
	v_max_f32_e32 v114, 0, v109
	v_max_f32_e32 v116, 0, v105
	v_max_f32_e32 v109, 0, v110
	v_max_f32_e32 v105, 0, v106
	v_max_f32_e32 v115, 0, v111
	v_max_f32_e32 v117, 0, v107
	v_max_f32_e32 v100, 0, v100
	v_max_f32_e32 v96, 0, v96
	v_max_f32_e32 v106, 0, v101
	v_max_f32_e32 v110, 0, v97
	v_max_f32_e32 v101, 0, v102
	v_max_f32_e32 v97, 0, v98
	v_max_f32_e32 v111, 0, v99
	v_pk_mul_f32 v[98:99], v[108:109], v[108:109]
	v_pk_mul_f32 v[104:105], v[104:105], v[104:105]
	v_max_f32_e32 v107, 0, v103
	v_pk_mul_f32 v[102:103], v[114:115], v[114:115]
	v_pk_mul_f32 v[108:109], v[116:117], v[116:117]
	v_pk_mul_f32 v[100:101], v[100:101], v[100:101]
	v_pk_mul_f32 v[96:97], v[96:97], v[96:97]
	v_bfe_u32 v118, v98, 16, 1
	v_bfe_u32 v119, v99, 16, 1
	v_bfe_u32 v120, v104, 16, 1
	v_bfe_u32 v121, v105, 16, 1
	v_pk_mul_f32 v[106:107], v[106:107], v[106:107]
	v_pk_mul_f32 v[110:111], v[110:111], v[110:111]
	v_bfe_u32 v114, v109, 16, 1
	v_bfe_u32 v115, v108, 16, 1
	v_bfe_u32 v116, v103, 16, 1
	v_bfe_u32 v117, v102, 16, 1
	v_bfe_u32 v126, v100, 16, 1
	v_bfe_u32 v127, v101, 16, 1
	v_bfe_u32 v128, v96, 16, 1
	v_bfe_u32 v129, v97, 16, 1
	v_add3_u32 v105, v105, v121, s96
	v_add3_u32 v104, v104, v120, s96
	v_add3_u32 v99, v99, v119, s96
	v_add3_u32 v98, v98, v118, s96
	v_bfe_u32 v122, v111, 16, 1
	v_bfe_u32 v123, v110, 16, 1
	v_bfe_u32 v124, v107, 16, 1
	v_bfe_u32 v125, v106, 16, 1
	v_add3_u32 v102, v102, v117, s96
	v_add3_u32 v103, v103, v116, s96
	v_add3_u32 v108, v108, v115, s96
	v_add3_u32 v109, v109, v114, s96
	v_add3_u32 v97, v97, v129, s96
	v_add3_u32 v96, v96, v128, s96
	v_add3_u32 v101, v101, v127, s96
	v_add3_u32 v100, v100, v126, s96
	v_lshrrev_b32_e32 v114, 16, v98
	v_lshrrev_b32_e32 v115, 16, v99
	v_lshrrev_b32_e32 v98, 16, v104
	v_lshrrev_b32_e32 v99, 16, v105
	v_add3_u32 v106, v106, v125, s96
	v_add3_u32 v107, v107, v124, s96
	v_add3_u32 v110, v110, v123, s96
	v_add3_u32 v111, v111, v122, s96
	v_lshrrev_b32_e32 v100, 16, v100
	v_lshrrev_b32_e32 v101, 16, v101
	v_lshrrev_b32_e32 v104, 16, v96
	v_lshrrev_b32_e32 v105, 16, v97
	v_and_or_b32 v99, v109, s97, v99
	v_and_or_b32 v98, v108, s97, v98
	v_and_or_b32 v97, v103, s97, v115
	v_and_or_b32 v96, v102, s97, v114
	global_store_dwordx4 v[112:113], v[96:99], off
	s_nop 1
	v_and_or_b32 v99, v111, s97, v105
	v_and_or_b32 v98, v110, s97, v104
	v_and_or_b32 v97, v107, s97, v101
	v_and_or_b32 v96, v106, s97, v100
	global_store_dwordx4 v[112:113], v[96:99], off offset:256
	s_nop 0
	s_nop 0
	v_or_b32_e32 v96, 48, v172
	v_ashrrev_i32_e32 v97, 31, v96
	v_lshlrev_b64 v[96:97], 13, v[96:97]
	v_lshl_add_u64 v[96:97], s[70:71], 0, v[96:97]
	v_lshl_add_u64 v[96:97], v[96:97], 0, v[174:175]
	s_nop 0
	v_fmamk_f32 v98, v186, 0x3a800000, v228
	v_rsq_f32_e32 v98, v98
	s_nop 0
	v_pk_fma_f32 v[94:95], v[94:95], v[98:99], v[86:87] op_sel_hi:[1,0,1]
	v_pk_fma_f32 v[92:93], v[92:93], v[98:99], v[84:85] op_sel_hi:[1,0,1]
	v_pk_fma_f32 v[90:91], v[90:91], v[98:99], v[82:83] op_sel_hi:[1,0,1]
	v_pk_fma_f32 v[88:89], v[88:89], v[98:99], v[80:81] op_sel_hi:[1,0,1]
	v_pk_fma_f32 v[70:71], v[70:71], v[98:99], v[78:79] op_sel_hi:[1,0,1]
	v_pk_fma_f32 v[68:69], v[68:69], v[98:99], v[76:77] op_sel_hi:[1,0,1]
	v_pk_fma_f32 v[66:67], v[66:67], v[98:99], v[74:75] op_sel_hi:[1,0,1]
	v_pk_fma_f32 v[64:65], v[64:65], v[98:99], v[72:73] op_sel_hi:[1,0,1]
	v_max_f32_e32 v92, 0, v92
	v_max_f32_e32 v88, 0, v88
	v_max_f32_e32 v98, 0, v93
	v_max_f32_e32 v100, 0, v89
	v_max_f32_e32 v93, 0, v94
	v_max_f32_e32 v89, 0, v90
	v_max_f32_e32 v68, 0, v68
	v_max_f32_e32 v64, 0, v64
	v_max_f32_e32 v90, 0, v69
	v_max_f32_e32 v94, 0, v65
	v_max_f32_e32 v69, 0, v70
	v_max_f32_e32 v65, 0, v66
	v_max_f32_e32 v99, 0, v95
	v_max_f32_e32 v101, 0, v91
	v_max_f32_e32 v91, 0, v71
	v_max_f32_e32 v95, 0, v67
	v_pk_mul_f32 v[66:67], v[92:93], v[92:93]
	v_pk_mul_f32 v[88:89], v[88:89], v[88:89]
	v_pk_mul_f32 v[68:69], v[68:69], v[68:69]
	v_pk_mul_f32 v[64:65], v[64:65], v[64:65]
	v_pk_mul_f32 v[70:71], v[98:99], v[98:99]
	v_pk_mul_f32 v[92:93], v[100:101], v[100:101]
	v_pk_mul_f32 v[90:91], v[90:91], v[90:91]
	v_pk_mul_f32 v[94:95], v[94:95], v[94:95]
	v_bfe_u32 v102, v66, 16, 1
	v_bfe_u32 v103, v67, 16, 1
	v_bfe_u32 v104, v88, 16, 1
	v_bfe_u32 v105, v89, 16, 1
	v_bfe_u32 v110, v68, 16, 1
	v_bfe_u32 v111, v69, 16, 1
	v_bfe_u32 v112, v64, 16, 1
	v_bfe_u32 v113, v65, 16, 1
	v_bfe_u32 v98, v93, 16, 1
	v_bfe_u32 v99, v92, 16, 1
	v_bfe_u32 v100, v71, 16, 1
	v_bfe_u32 v101, v70, 16, 1
	v_bfe_u32 v106, v95, 16, 1
	v_bfe_u32 v107, v94, 16, 1
	v_bfe_u32 v108, v91, 16, 1
	v_bfe_u32 v109, v90, 16, 1
	v_add3_u32 v89, v89, v105, s96
	v_add3_u32 v88, v88, v104, s96
	v_add3_u32 v67, v67, v103, s96
	v_add3_u32 v66, v66, v102, s96
	v_add3_u32 v65, v65, v113, s96
	v_add3_u32 v64, v64, v112, s96
	v_add3_u32 v69, v69, v111, s96
	v_add3_u32 v68, v68, v110, s96
	v_add3_u32 v70, v70, v101, s96
	v_add3_u32 v71, v71, v100, s96
	v_add3_u32 v92, v92, v99, s96
	v_add3_u32 v93, v93, v98, s96
	v_add3_u32 v90, v90, v109, s96
	v_add3_u32 v91, v91, v108, s96
	v_add3_u32 v94, v94, v107, s96
	v_add3_u32 v95, v95, v106, s96
	v_lshrrev_b32_e32 v98, 16, v66
	v_lshrrev_b32_e32 v99, 16, v67
	v_lshrrev_b32_e32 v66, 16, v88
	v_lshrrev_b32_e32 v67, 16, v89
	v_lshrrev_b32_e32 v68, 16, v68
	v_lshrrev_b32_e32 v69, 16, v69
	v_lshrrev_b32_e32 v88, 16, v64
	v_lshrrev_b32_e32 v89, 16, v65
	v_and_or_b32 v67, v93, s97, v67
	v_and_or_b32 v66, v92, s97, v66
	v_and_or_b32 v65, v71, s97, v99
	v_and_or_b32 v64, v70, s97, v98
	v_and_or_b32 v71, v95, s97, v89
	v_and_or_b32 v70, v94, s97, v88
	v_and_or_b32 v69, v91, s97, v69
	v_and_or_b32 v68, v90, s97, v68
	global_store_dwordx4 v[96:97], v[64:67], off
	global_store_dwordx4 v[96:97], v[68:71], off offset:256
	s_nop 0
	v_lshl_add_u64 v[64:65], v[168:169], 0, s[18:19]
	v_add_co_u32_e32 v68, vcc, s11, v168
	s_mov_b32 s11, 0x120000
	s_nop 0
	v_addc_co_u32_e32 v69, vcc, 0, v169, vcc
	s_mov_b64 s[18:19], 0x120000
	s_nop 0
	v_fmamk_f32 v66, v187, 0x3a800000, v228
	v_rsq_f32_e32 v66, v66
	s_nop 0
	v_pk_fma_f32 v[62:63], v[62:63], v[66:67], v[86:87] op_sel_hi:[1,0,1]
	v_pk_fma_f32 v[60:61], v[60:61], v[66:67], v[84:85] op_sel_hi:[1,0,1]
	v_pk_fma_f32 v[58:59], v[58:59], v[66:67], v[82:83] op_sel_hi:[1,0,1]
	v_pk_fma_f32 v[56:57], v[56:57], v[66:67], v[80:81] op_sel_hi:[1,0,1]
	v_pk_fma_f32 v[54:55], v[54:55], v[66:67], v[78:79] op_sel_hi:[1,0,1]
	v_pk_fma_f32 v[52:53], v[52:53], v[66:67], v[76:77] op_sel_hi:[1,0,1]
	v_pk_fma_f32 v[50:51], v[50:51], v[66:67], v[74:75] op_sel_hi:[1,0,1]
	v_pk_fma_f32 v[48:49], v[48:49], v[66:67], v[72:73] op_sel_hi:[1,0,1]
	v_max_f32_e32 v60, 0, v60
	v_max_f32_e32 v56, 0, v56
	v_max_f32_e32 v66, 0, v61
	v_max_f32_e32 v70, 0, v57
	v_max_f32_e32 v61, 0, v62
	v_max_f32_e32 v57, 0, v58
	v_max_f32_e32 v67, 0, v63
	v_max_f32_e32 v71, 0, v59
	v_max_f32_e32 v52, 0, v52
	v_max_f32_e32 v48, 0, v48
	v_max_f32_e32 v58, 0, v53
	v_max_f32_e32 v62, 0, v49
	v_max_f32_e32 v53, 0, v54
	v_max_f32_e32 v49, 0, v50
	v_max_f32_e32 v63, 0, v51
	v_pk_mul_f32 v[50:51], v[60:61], v[60:61]
	v_pk_mul_f32 v[56:57], v[56:57], v[56:57]
	v_max_f32_e32 v59, 0, v55
	v_pk_mul_f32 v[54:55], v[66:67], v[66:67]
	v_pk_mul_f32 v[60:61], v[70:71], v[70:71]
	v_pk_mul_f32 v[52:53], v[52:53], v[52:53]
	v_pk_mul_f32 v[48:49], v[48:49], v[48:49]
	v_bfe_u32 v88, v50, 16, 1
	v_bfe_u32 v89, v51, 16, 1
	v_bfe_u32 v90, v56, 16, 1
	v_bfe_u32 v91, v57, 16, 1
	v_pk_mul_f32 v[58:59], v[58:59], v[58:59]
	v_pk_mul_f32 v[62:63], v[62:63], v[62:63]
	v_bfe_u32 v66, v61, 16, 1
	v_bfe_u32 v67, v60, 16, 1
	v_bfe_u32 v70, v55, 16, 1
	v_bfe_u32 v71, v54, 16, 1
	v_bfe_u32 v96, v52, 16, 1
	v_bfe_u32 v97, v53, 16, 1
	v_bfe_u32 v98, v48, 16, 1
	v_bfe_u32 v99, v49, 16, 1
	v_add3_u32 v57, v57, v91, s96
	v_add3_u32 v56, v56, v90, s96
	v_add3_u32 v51, v51, v89, s96
	v_add3_u32 v50, v50, v88, s96
	v_bfe_u32 v92, v63, 16, 1
	v_bfe_u32 v93, v62, 16, 1
	v_bfe_u32 v94, v59, 16, 1
	v_bfe_u32 v95, v58, 16, 1
	v_add3_u32 v54, v54, v71, s96
	v_add3_u32 v55, v55, v70, s96
	v_add3_u32 v60, v60, v67, s96
	v_add3_u32 v61, v61, v66, s96
	v_add3_u32 v49, v49, v99, s96
	v_add3_u32 v48, v48, v98, s96
	v_add3_u32 v53, v53, v97, s96
	v_add3_u32 v52, v52, v96, s96
	v_lshrrev_b32_e32 v66, 16, v50
	v_lshrrev_b32_e32 v67, 16, v51
	v_lshrrev_b32_e32 v50, 16, v56
	v_lshrrev_b32_e32 v51, 16, v57
	v_add3_u32 v58, v58, v95, s96
	v_add3_u32 v59, v59, v94, s96
	v_add3_u32 v62, v62, v93, s96
	v_add3_u32 v63, v63, v92, s96
	v_lshrrev_b32_e32 v52, 16, v52
	v_lshrrev_b32_e32 v53, 16, v53
	v_lshrrev_b32_e32 v56, 16, v48
	v_lshrrev_b32_e32 v57, 16, v49
	v_and_or_b32 v51, v61, s97, v51
	v_and_or_b32 v50, v60, s97, v50
	v_and_or_b32 v49, v55, s97, v67
	v_and_or_b32 v48, v54, s97, v66
	v_and_or_b32 v55, v63, s97, v57
	v_and_or_b32 v54, v62, s97, v56
	v_and_or_b32 v53, v59, s97, v53
	v_and_or_b32 v52, v58, s97, v52
	global_store_dwordx4 v[68:69], v[48:51], off
	global_store_dwordx4 v[64:65], v[52:55], off offset:256
	s_nop 0
	v_lshl_add_u64 v[48:49], v[168:169], 0, s[18:19]
	v_add_co_u32_e32 v52, vcc, s11, v168
	s_mov_b32 s11, 0x140000
	s_nop 0
	v_addc_co_u32_e32 v53, vcc, 0, v169, vcc
	s_mov_b64 s[18:19], 0x140000
	s_nop 0
	v_fmamk_f32 v50, v188, 0x3a800000, v228
	v_rsq_f32_e32 v50, v50
	s_nop 0
	v_pk_fma_f32 v[46:47], v[46:47], v[50:51], v[86:87] op_sel_hi:[1,0,1]
	v_pk_fma_f32 v[44:45], v[44:45], v[50:51], v[84:85] op_sel_hi:[1,0,1]
	v_pk_fma_f32 v[42:43], v[42:43], v[50:51], v[82:83] op_sel_hi:[1,0,1]
	v_pk_fma_f32 v[40:41], v[40:41], v[50:51], v[80:81] op_sel_hi:[1,0,1]
	v_pk_fma_f32 v[38:39], v[38:39], v[50:51], v[78:79] op_sel_hi:[1,0,1]
	v_pk_fma_f32 v[36:37], v[36:37], v[50:51], v[76:77] op_sel_hi:[1,0,1]
	v_pk_fma_f32 v[34:35], v[34:35], v[50:51], v[74:75] op_sel_hi:[1,0,1]
	v_pk_fma_f32 v[32:33], v[32:33], v[50:51], v[72:73] op_sel_hi:[1,0,1]
	v_max_f32_e32 v44, 0, v44
	v_max_f32_e32 v40, 0, v40
	v_max_f32_e32 v50, 0, v45
	v_max_f32_e32 v54, 0, v41
	v_max_f32_e32 v45, 0, v46
	v_max_f32_e32 v41, 0, v42
	v_max_f32_e32 v51, 0, v47
	v_max_f32_e32 v55, 0, v43
	v_max_f32_e32 v36, 0, v36
	v_max_f32_e32 v32, 0, v32
	v_max_f32_e32 v42, 0, v37
	v_max_f32_e32 v46, 0, v33
	v_max_f32_e32 v37, 0, v38
	v_max_f32_e32 v33, 0, v34
	v_max_f32_e32 v47, 0, v35
	v_pk_mul_f32 v[34:35], v[44:45], v[44:45]
	v_pk_mul_f32 v[40:41], v[40:41], v[40:41]
	v_max_f32_e32 v43, 0, v39
	v_pk_mul_f32 v[38:39], v[50:51], v[50:51]
	v_pk_mul_f32 v[44:45], v[54:55], v[54:55]
	v_pk_mul_f32 v[36:37], v[36:37], v[36:37]
	v_pk_mul_f32 v[32:33], v[32:33], v[32:33]
	v_bfe_u32 v56, v34, 16, 1
	v_bfe_u32 v57, v35, 16, 1
	v_bfe_u32 v58, v40, 16, 1
	v_bfe_u32 v59, v41, 16, 1
	v_pk_mul_f32 v[42:43], v[42:43], v[42:43]
	v_pk_mul_f32 v[46:47], v[46:47], v[46:47]
	v_bfe_u32 v50, v45, 16, 1
	v_bfe_u32 v51, v44, 16, 1
	v_bfe_u32 v54, v39, 16, 1
	v_bfe_u32 v55, v38, 16, 1
	v_bfe_u32 v64, v36, 16, 1
	v_bfe_u32 v65, v37, 16, 1
	v_bfe_u32 v66, v32, 16, 1
	v_bfe_u32 v67, v33, 16, 1
	v_add3_u32 v41, v41, v59, s96
	v_add3_u32 v40, v40, v58, s96
	v_add3_u32 v35, v35, v57, s96
	v_add3_u32 v34, v34, v56, s96
	v_bfe_u32 v60, v47, 16, 1
	v_bfe_u32 v61, v46, 16, 1
	v_bfe_u32 v62, v43, 16, 1
	v_bfe_u32 v63, v42, 16, 1
	v_add3_u32 v38, v38, v55, s96
	v_add3_u32 v39, v39, v54, s96
	v_add3_u32 v44, v44, v51, s96
	v_add3_u32 v45, v45, v50, s96
	v_add3_u32 v33, v33, v67, s96
	v_add3_u32 v32, v32, v66, s96
	v_add3_u32 v37, v37, v65, s96
	v_add3_u32 v36, v36, v64, s96
	v_lshrrev_b32_e32 v50, 16, v34
	v_lshrrev_b32_e32 v51, 16, v35
	v_lshrrev_b32_e32 v34, 16, v40
	v_lshrrev_b32_e32 v35, 16, v41
	v_add3_u32 v42, v42, v63, s96
	v_add3_u32 v43, v43, v62, s96
	v_add3_u32 v46, v46, v61, s96
	v_add3_u32 v47, v47, v60, s96
	v_lshrrev_b32_e32 v36, 16, v36
	v_lshrrev_b32_e32 v37, 16, v37
	v_lshrrev_b32_e32 v40, 16, v32
	v_lshrrev_b32_e32 v41, 16, v33
	v_and_or_b32 v35, v45, s97, v35
	v_and_or_b32 v34, v44, s97, v34
	v_and_or_b32 v33, v39, s97, v51
	v_and_or_b32 v32, v38, s97, v50
	v_and_or_b32 v39, v47, s97, v41
	v_and_or_b32 v38, v46, s97, v40
	v_and_or_b32 v37, v43, s97, v37
	v_and_or_b32 v36, v42, s97, v36
	global_store_dwordx4 v[52:53], v[32:35], off
	global_store_dwordx4 v[48:49], v[36:39], off offset:256
	s_nop 0
	v_lshl_add_u64 v[32:33], v[168:169], 0, s[18:19]
	v_add_co_u32_e32 v36, vcc, s11, v168
	s_mov_b32 s11, 0x160000
	s_nop 0
	v_addc_co_u32_e32 v37, vcc, 0, v169, vcc
	s_mov_b64 s[18:19], 0x160000
	s_nop 0
	v_fmamk_f32 v34, v189, 0x3a800000, v228
	v_rsq_f32_e32 v34, v34
	s_nop 0
	v_pk_fma_f32 v[30:31], v[30:31], v[34:35], v[86:87] op_sel_hi:[1,0,1]
	v_pk_fma_f32 v[28:29], v[28:29], v[34:35], v[84:85] op_sel_hi:[1,0,1]
	v_pk_fma_f32 v[26:27], v[26:27], v[34:35], v[82:83] op_sel_hi:[1,0,1]
	v_pk_fma_f32 v[24:25], v[24:25], v[34:35], v[80:81] op_sel_hi:[1,0,1]
	v_pk_fma_f32 v[22:23], v[22:23], v[34:35], v[78:79] op_sel_hi:[1,0,1]
	v_pk_fma_f32 v[20:21], v[20:21], v[34:35], v[76:77] op_sel_hi:[1,0,1]
	v_pk_fma_f32 v[18:19], v[18:19], v[34:35], v[74:75] op_sel_hi:[1,0,1]
	v_pk_fma_f32 v[16:17], v[16:17], v[34:35], v[72:73] op_sel_hi:[1,0,1]
	v_max_f32_e32 v28, 0, v28
	v_max_f32_e32 v24, 0, v24
	v_max_f32_e32 v34, 0, v29
	v_max_f32_e32 v38, 0, v25
	v_max_f32_e32 v29, 0, v30
	v_max_f32_e32 v25, 0, v26
	v_max_f32_e32 v35, 0, v31
	v_max_f32_e32 v39, 0, v27
	v_max_f32_e32 v20, 0, v20
	v_max_f32_e32 v16, 0, v16
	v_max_f32_e32 v26, 0, v21
	v_max_f32_e32 v30, 0, v17
	v_max_f32_e32 v21, 0, v22
	v_max_f32_e32 v17, 0, v18
	v_max_f32_e32 v31, 0, v19
	v_pk_mul_f32 v[18:19], v[28:29], v[28:29]
	v_pk_mul_f32 v[24:25], v[24:25], v[24:25]
	v_max_f32_e32 v27, 0, v23
	v_pk_mul_f32 v[22:23], v[34:35], v[34:35]
	v_pk_mul_f32 v[28:29], v[38:39], v[38:39]
	v_pk_mul_f32 v[20:21], v[20:21], v[20:21]
	v_pk_mul_f32 v[16:17], v[16:17], v[16:17]
	v_bfe_u32 v40, v18, 16, 1
	v_bfe_u32 v41, v19, 16, 1
	v_bfe_u32 v42, v24, 16, 1
	v_bfe_u32 v43, v25, 16, 1
	v_pk_mul_f32 v[26:27], v[26:27], v[26:27]
	v_pk_mul_f32 v[30:31], v[30:31], v[30:31]
	v_bfe_u32 v34, v29, 16, 1
	v_bfe_u32 v35, v28, 16, 1
	v_bfe_u32 v38, v23, 16, 1
	v_bfe_u32 v39, v22, 16, 1
	v_bfe_u32 v48, v20, 16, 1
	v_bfe_u32 v49, v21, 16, 1
	v_bfe_u32 v50, v16, 16, 1
	v_bfe_u32 v51, v17, 16, 1
	v_add3_u32 v25, v25, v43, s96
	v_add3_u32 v24, v24, v42, s96
	v_add3_u32 v19, v19, v41, s96
	v_add3_u32 v18, v18, v40, s96
	v_bfe_u32 v44, v31, 16, 1
	v_bfe_u32 v45, v30, 16, 1
	v_bfe_u32 v46, v27, 16, 1
	v_bfe_u32 v47, v26, 16, 1
	v_add3_u32 v22, v22, v39, s96
	v_add3_u32 v23, v23, v38, s96
	v_add3_u32 v28, v28, v35, s96
	v_add3_u32 v29, v29, v34, s96
	v_add3_u32 v17, v17, v51, s96
	v_add3_u32 v16, v16, v50, s96
	v_add3_u32 v21, v21, v49, s96
	v_add3_u32 v20, v20, v48, s96
	v_lshrrev_b32_e32 v34, 16, v18
	v_lshrrev_b32_e32 v35, 16, v19
	v_lshrrev_b32_e32 v18, 16, v24
	v_lshrrev_b32_e32 v19, 16, v25
	v_add3_u32 v26, v26, v47, s96
	v_add3_u32 v27, v27, v46, s96
	v_add3_u32 v30, v30, v45, s96
	v_add3_u32 v31, v31, v44, s96
	v_lshrrev_b32_e32 v20, 16, v20
	v_lshrrev_b32_e32 v21, 16, v21
	v_lshrrev_b32_e32 v24, 16, v16
	v_lshrrev_b32_e32 v25, 16, v17
	v_and_or_b32 v19, v29, s97, v19
	v_and_or_b32 v18, v28, s97, v18
	v_and_or_b32 v17, v23, s97, v35
	v_and_or_b32 v16, v22, s97, v34
	v_and_or_b32 v23, v31, s97, v25
	v_and_or_b32 v22, v30, s97, v24
	v_and_or_b32 v21, v27, s97, v21
	v_and_or_b32 v20, v26, s97, v20
	global_store_dwordx4 v[36:37], v[16:19], off
	global_store_dwordx4 v[32:33], v[20:23], off offset:256
	s_nop 0
	v_lshl_add_u64 v[16:17], v[168:169], 0, s[18:19]
	v_add_co_u32_e32 v20, vcc, s11, v168
	s_nop 0
	v_fmamk_f32 v18, v190, 0x3a800000, v228
	v_rsq_f32_e32 v18, v18
	v_addc_co_u32_e32 v21, vcc, 0, v169, vcc
	s_andn2_b64 vcc, exec, s[2:3]
	v_pk_fma_f32 v[14:15], v[14:15], v[18:19], v[86:87] op_sel_hi:[1,0,1]
	v_pk_fma_f32 v[12:13], v[12:13], v[18:19], v[84:85] op_sel_hi:[1,0,1]
	v_pk_fma_f32 v[10:11], v[10:11], v[18:19], v[82:83] op_sel_hi:[1,0,1]
	v_pk_fma_f32 v[8:9], v[8:9], v[18:19], v[80:81] op_sel_hi:[1,0,1]
	v_pk_fma_f32 v[6:7], v[6:7], v[18:19], v[78:79] op_sel_hi:[1,0,1]
	v_pk_fma_f32 v[4:5], v[4:5], v[18:19], v[76:77] op_sel_hi:[1,0,1]
	v_pk_fma_f32 v[2:3], v[2:3], v[18:19], v[74:75] op_sel_hi:[1,0,1]
	v_pk_fma_f32 v[0:1], v[0:1], v[18:19], v[72:73] op_sel_hi:[1,0,1]
	v_max_f32_e32 v12, 0, v12
	v_max_f32_e32 v8, 0, v8
	v_max_f32_e32 v18, 0, v13
	v_max_f32_e32 v22, 0, v9
	v_max_f32_e32 v13, 0, v14
	v_max_f32_e32 v9, 0, v10
	v_max_f32_e32 v19, 0, v15
	v_max_f32_e32 v23, 0, v11
	v_max_f32_e32 v4, 0, v4
	v_max_f32_e32 v0, 0, v0
	v_max_f32_e32 v10, 0, v5
	v_max_f32_e32 v14, 0, v1
	v_max_f32_e32 v5, 0, v6
	v_max_f32_e32 v1, 0, v2
	v_max_f32_e32 v15, 0, v3
	v_pk_mul_f32 v[2:3], v[12:13], v[12:13]
	v_pk_mul_f32 v[8:9], v[8:9], v[8:9]
	v_max_f32_e32 v11, 0, v7
	v_pk_mul_f32 v[6:7], v[18:19], v[18:19]
	v_pk_mul_f32 v[12:13], v[22:23], v[22:23]
	v_pk_mul_f32 v[4:5], v[4:5], v[4:5]
	v_pk_mul_f32 v[0:1], v[0:1], v[0:1]
	v_bfe_u32 v24, v2, 16, 1
	v_bfe_u32 v25, v3, 16, 1
	v_bfe_u32 v26, v8, 16, 1
	v_bfe_u32 v27, v9, 16, 1
	v_pk_mul_f32 v[10:11], v[10:11], v[10:11]
	v_pk_mul_f32 v[14:15], v[14:15], v[14:15]
	v_bfe_u32 v18, v13, 16, 1
	v_bfe_u32 v19, v12, 16, 1
	v_bfe_u32 v22, v7, 16, 1
	v_bfe_u32 v23, v6, 16, 1
	v_bfe_u32 v32, v4, 16, 1
	v_bfe_u32 v33, v5, 16, 1
	v_bfe_u32 v34, v0, 16, 1
	v_bfe_u32 v35, v1, 16, 1
	v_add3_u32 v9, v9, v27, s96
	v_add3_u32 v8, v8, v26, s96
	v_add3_u32 v3, v3, v25, s96
	v_add3_u32 v2, v2, v24, s96
	v_bfe_u32 v28, v15, 16, 1
	v_bfe_u32 v29, v14, 16, 1
	v_bfe_u32 v30, v11, 16, 1
	v_bfe_u32 v31, v10, 16, 1
	v_add3_u32 v6, v6, v23, s96
	v_add3_u32 v7, v7, v22, s96
	v_add3_u32 v12, v12, v19, s96
	v_add3_u32 v13, v13, v18, s96
	v_add3_u32 v1, v1, v35, s96
	v_add3_u32 v0, v0, v34, s96
	v_add3_u32 v5, v5, v33, s96
	v_add3_u32 v4, v4, v32, s96
	v_lshrrev_b32_e32 v18, 16, v2
	v_lshrrev_b32_e32 v19, 16, v3
	v_lshrrev_b32_e32 v2, 16, v8
	v_lshrrev_b32_e32 v3, 16, v9
	v_add3_u32 v10, v10, v31, s96
	v_add3_u32 v11, v11, v30, s96
	v_add3_u32 v14, v14, v29, s96
	v_add3_u32 v15, v15, v28, s96
	v_lshrrev_b32_e32 v4, 16, v4
	v_lshrrev_b32_e32 v5, 16, v5
	v_lshrrev_b32_e32 v8, 16, v0
	v_lshrrev_b32_e32 v9, 16, v1
	v_and_or_b32 v3, v13, s97, v3
	v_and_or_b32 v2, v12, s97, v2
	v_and_or_b32 v1, v7, s97, v19
	v_and_or_b32 v0, v6, s97, v18
	s_mov_b64 s[2:3], -1
	v_and_or_b32 v7, v15, s97, v9
	v_and_or_b32 v6, v14, s97, v8
	v_and_or_b32 v5, v11, s97, v5
	v_and_or_b32 v4, v10, s97, v4
	global_store_dwordx4 v[20:21], v[0:3], off
	global_store_dwordx4 v[16:17], v[4:7], off offset:256
	s_cbranch_vccnz .LBB0_1172
	s_andn2_b64 vcc, exec, s[4:5]
	s_cbranch_vccnz .LBB0_1171
	s_barrier
	s_branch .LBB0_1171

.LBB0_1365:
	s_lshr_b32 s8, s21, 3
	s_mul_hi_u32 s9, s8, 0x6000
	s_mulk_i32 s8, 0x6000
	s_add_u32 s8, s37, s8
	s_addc_u32 s9, s39, s9
	v_lshl_add_u32 v176, s21, 8, v172
	v_lshl_add_u64 v[32:33], s[8:9], 0, v[168:169]
	s_mov_b64 s[8:9], 0x5000
	v_ashrrev_i32_e32 v177, 31, v176
	v_lshl_add_u64 v[36:37], v[32:33], 0, s[8:9]
	s_movk_i32 s8, 0x5000
	v_lshlrev_b64 v[154:155], 12, v[176:177]
	v_add_co_u32_e32 v32, vcc, s8, v32
	v_lshl_add_u64 v[154:155], s[74:75], 0, v[154:155]
	s_nop 0
	v_addc_co_u32_e32 v33, vcc, 0, v33, vcc
	v_lshl_add_u64 v[170:171], v[154:155], 0, v[168:169]
	global_load_dwordx4 v[72:75], v[32:33], off
	global_load_dwordx4 v[76:79], v[36:37], off offset:16
	s_nop 0
	global_load_dwordx4 v[32:35], v[36:37], off offset:528
	s_nop 0
	global_load_dwordx4 v[36:39], v[36:37], off offset:512
	s_nop 0
	global_load_dwordx4 v[184:187], v[170:171], off
	global_load_dwordx4 v[188:191], v[170:171], off offset:16
	global_load_dwordx4 v[192:195], v[170:171], off offset:512
	global_load_dwordx4 v[196:199], v[170:171], off offset:528
	s_mov_b64 s[8:9], 0x10000
	v_lshl_add_u64 v[178:179], v[170:171], 0, s[8:9]
	global_load_dwordx4 v[208:211], v[178:179], off
	global_load_dwordx4 v[212:215], v[178:179], off offset:16
	global_load_dwordx4 v[216:219], v[178:179], off offset:512
	global_load_dwordx4 v[220:223], v[178:179], off offset:528
	s_waitcnt vmcnt(4)
	v_pk_fma_f32 v[140:141], v[140:141], v[72:73], v[184:185]
	v_pk_fma_f32 v[142:143], v[142:143], v[74:75], v[186:187]
	v_pk_fma_f32 v[136:137], v[136:137], v[76:77], v[188:189]
	v_pk_fma_f32 v[138:139], v[138:139], v[78:79], v[190:191]
	v_pk_fma_f32 v[132:133], v[132:133], v[36:37], v[192:193]
	v_pk_fma_f32 v[134:135], v[134:135], v[38:39], v[194:195]
	v_pk_fma_f32 v[128:129], v[128:129], v[32:33], v[196:197]
	v_pk_fma_f32 v[130:131], v[130:131], v[34:35], v[198:199]
	global_store_dwordx4 v[170:171], v[140:143], off
	global_store_dwordx4 v[170:171], v[136:139], off offset:16
	global_store_dwordx4 v[170:171], v[132:135], off offset:512
	global_store_dwordx4 v[170:171], v[128:131], off offset:528
	s_mov_b64 s[8:9], 0x20000
	v_lshl_add_u64 v[180:181], v[170:171], 0, s[8:9]
	global_load_dwordx4 v[184:187], v[180:181], off
	global_load_dwordx4 v[188:191], v[180:181], off offset:16
	global_load_dwordx4 v[192:195], v[180:181], off offset:512
	global_load_dwordx4 v[196:199], v[180:181], off offset:528
	s_waitcnt vmcnt(8)
	v_pk_fma_f32 v[124:125], v[124:125], v[72:73], v[208:209]
	v_pk_fma_f32 v[126:127], v[126:127], v[74:75], v[210:211]
	v_pk_fma_f32 v[120:121], v[120:121], v[76:77], v[212:213]
	v_pk_fma_f32 v[122:123], v[122:123], v[78:79], v[214:215]
	v_pk_fma_f32 v[108:109], v[108:109], v[36:37], v[216:217]
	v_pk_fma_f32 v[110:111], v[110:111], v[38:39], v[218:219]
	v_pk_fma_f32 v[104:105], v[104:105], v[32:33], v[220:221]
	v_pk_fma_f32 v[106:107], v[106:107], v[34:35], v[222:223]
	global_store_dwordx4 v[178:179], v[124:127], off
	global_store_dwordx4 v[178:179], v[120:123], off offset:16
	global_store_dwordx4 v[178:179], v[108:111], off offset:512
	global_store_dwordx4 v[178:179], v[104:107], off offset:528
	s_mov_b64 s[8:9], 0x30000
	v_lshl_add_u64 v[176:177], v[170:171], 0, s[8:9]
	global_load_dwordx4 v[208:211], v[176:177], off
	global_load_dwordx4 v[212:215], v[176:177], off offset:16
	global_load_dwordx4 v[216:219], v[176:177], off offset:512
	global_load_dwordx4 v[220:223], v[176:177], off offset:528
	s_waitcnt vmcnt(8)
	v_pk_fma_f32 v[116:117], v[116:117], v[72:73], v[184:185]
	v_pk_fma_f32 v[118:119], v[118:119], v[74:75], v[186:187]
	v_pk_fma_f32 v[112:113], v[112:113], v[76:77], v[188:189]
	v_pk_fma_f32 v[114:115], v[114:115], v[78:79], v[190:191]
	v_pk_fma_f32 v[92:93], v[92:93], v[36:37], v[192:193]
	v_pk_fma_f32 v[94:95], v[94:95], v[38:39], v[194:195]
	v_pk_fma_f32 v[88:89], v[88:89], v[32:33], v[196:197]
	v_pk_fma_f32 v[90:91], v[90:91], v[34:35], v[198:199]
	global_store_dwordx4 v[180:181], v[116:119], off
	global_store_dwordx4 v[180:181], v[112:115], off offset:16
	global_store_dwordx4 v[180:181], v[92:95], off offset:512
	global_store_dwordx4 v[180:181], v[88:91], off offset:528
	s_mov_b64 s[8:9], 0x80000
	v_lshl_add_u64 v[178:179], v[170:171], 0, s[8:9]
	global_load_dwordx4 v[184:187], v[178:179], off
	global_load_dwordx4 v[188:191], v[178:179], off offset:16
	global_load_dwordx4 v[192:195], v[178:179], off offset:512
	global_load_dwordx4 v[196:199], v[178:179], off offset:528
	s_waitcnt vmcnt(8)
	v_pk_fma_f32 v[100:101], v[100:101], v[72:73], v[208:209]
	v_pk_fma_f32 v[102:103], v[102:103], v[74:75], v[210:211]
	v_pk_fma_f32 v[96:97], v[96:97], v[76:77], v[212:213]
	v_pk_fma_f32 v[98:99], v[98:99], v[78:79], v[214:215]
	v_pk_fma_f32 v[84:85], v[84:85], v[36:37], v[216:217]
	v_pk_fma_f32 v[86:87], v[86:87], v[38:39], v[218:219]
	v_pk_fma_f32 v[80:81], v[80:81], v[32:33], v[220:221]
	v_pk_fma_f32 v[82:83], v[82:83], v[34:35], v[222:223]
	global_store_dwordx4 v[176:177], v[100:103], off
	global_store_dwordx4 v[176:177], v[96:99], off offset:16
	global_store_dwordx4 v[176:177], v[84:87], off offset:512
	global_store_dwordx4 v[176:177], v[80:83], off offset:528
	s_mov_b64 s[8:9], 0x90000
	v_lshl_add_u64 v[180:181], v[170:171], 0, s[8:9]
	global_load_dwordx4 v[208:211], v[180:181], off
	global_load_dwordx4 v[212:215], v[180:181], off offset:16
	global_load_dwordx4 v[216:219], v[180:181], off offset:512
	global_load_dwordx4 v[220:223], v[180:181], off offset:528
	s_waitcnt vmcnt(8)
	v_pk_fma_f32 v[68:69], v[68:69], v[72:73], v[184:185]
	v_pk_fma_f32 v[70:71], v[70:71], v[74:75], v[186:187]
	v_pk_fma_f32 v[64:65], v[64:65], v[76:77], v[188:189]
	v_pk_fma_f32 v[66:67], v[66:67], v[78:79], v[190:191]
	v_pk_fma_f32 v[52:53], v[52:53], v[36:37], v[192:193]
	v_pk_fma_f32 v[54:55], v[54:55], v[38:39], v[194:195]
	v_pk_fma_f32 v[48:49], v[48:49], v[32:33], v[196:197]
	v_pk_fma_f32 v[50:51], v[50:51], v[34:35], v[198:199]
	global_store_dwordx4 v[178:179], v[68:71], off
	global_store_dwordx4 v[178:179], v[64:67], off offset:16
	global_store_dwordx4 v[178:179], v[52:55], off offset:512
	global_store_dwordx4 v[178:179], v[48:51], off offset:528
	s_mov_b64 s[8:9], 0xa0000
	v_lshl_add_u64 v[176:177], v[170:171], 0, s[8:9]
	global_load_dwordx4 v[184:187], v[176:177], off
	global_load_dwordx4 v[188:191], v[176:177], off offset:16
	global_load_dwordx4 v[192:195], v[176:177], off offset:512
	global_load_dwordx4 v[196:199], v[176:177], off offset:528
	s_waitcnt vmcnt(8)
	v_pk_fma_f32 v[60:61], v[60:61], v[72:73], v[208:209]
	v_pk_fma_f32 v[62:63], v[62:63], v[74:75], v[210:211]
	v_pk_fma_f32 v[56:57], v[56:57], v[76:77], v[212:213]
	v_pk_fma_f32 v[58:59], v[58:59], v[78:79], v[214:215]
	v_pk_fma_f32 v[44:45], v[44:45], v[36:37], v[216:217]
	v_pk_fma_f32 v[46:47], v[46:47], v[38:39], v[218:219]
	v_pk_fma_f32 v[40:41], v[40:41], v[32:33], v[220:221]
	v_pk_fma_f32 v[42:43], v[42:43], v[34:35], v[222:223]
	global_store_dwordx4 v[180:181], v[60:63], off
	global_store_dwordx4 v[180:181], v[56:59], off offset:16
	global_store_dwordx4 v[180:181], v[44:47], off offset:512
	global_store_dwordx4 v[180:181], v[40:43], off offset:528
	s_mov_b64 s[8:9], 0xb0000
	v_lshl_add_u64 v[178:179], v[170:171], 0, s[8:9]
	global_load_dwordx4 v[208:211], v[178:179], off
	global_load_dwordx4 v[212:215], v[178:179], off offset:16
	global_load_dwordx4 v[216:219], v[178:179], off offset:512
	global_load_dwordx4 v[220:223], v[178:179], off offset:528
	s_waitcnt vmcnt(8)
	v_pk_fma_f32 v[28:29], v[28:29], v[72:73], v[184:185]
	v_pk_fma_f32 v[30:31], v[30:31], v[74:75], v[186:187]
	v_pk_fma_f32 v[24:25], v[24:25], v[76:77], v[188:189]
	v_pk_fma_f32 v[26:27], v[26:27], v[78:79], v[190:191]
	v_pk_fma_f32 v[20:21], v[20:21], v[36:37], v[192:193]
	v_pk_fma_f32 v[22:23], v[22:23], v[38:39], v[194:195]
	v_pk_fma_f32 v[16:17], v[16:17], v[32:33], v[196:197]
	v_pk_fma_f32 v[18:19], v[18:19], v[34:35], v[198:199]
	global_store_dwordx4 v[176:177], v[28:31], off
	global_store_dwordx4 v[176:177], v[24:27], off offset:16
	global_store_dwordx4 v[176:177], v[20:23], off offset:512
	global_store_dwordx4 v[176:177], v[16:19], off offset:528
	s_waitcnt vmcnt(4)
	v_pk_fma_f32 v[12:13], v[12:13], v[72:73], v[208:209]
	v_pk_fma_f32 v[14:15], v[14:15], v[74:75], v[210:211]
	v_pk_fma_f32 v[8:9], v[8:9], v[76:77], v[212:213]
	v_pk_fma_f32 v[10:11], v[10:11], v[78:79], v[214:215]
	v_pk_fma_f32 v[4:5], v[4:5], v[36:37], v[216:217]
	v_pk_fma_f32 v[6:7], v[6:7], v[38:39], v[218:219]
	v_pk_fma_f32 v[0:1], v[0:1], v[32:33], v[220:221]
	v_pk_fma_f32 v[2:3], v[2:3], v[34:35], v[222:223]
	global_store_dwordx4 v[178:179], v[12:15], off
	global_store_dwordx4 v[178:179], v[8:11], off offset:16
	global_store_dwordx4 v[178:179], v[4:7], off offset:512
	global_store_dwordx4 v[178:179], v[0:3], off offset:528
	s_mov_b64 s[8:9], -1
	s_andn2_b64 vcc, exec, s[6:7]
	s_cbranch_vccnz .LBB0_1360
	s_andn2_b64 vcc, exec, s[0:1]
	s_cbranch_vccnz .LBB0_1359
	s_barrier
	s_branch .LBB0_1359

	.amdhsa_kernel _Z8mega_fwd4Args
		.amdhsa_group_segment_fixed_size 0
		.amdhsa_private_segment_fixed_size 0
		.amdhsa_kernarg_size 456
		.amdhsa_user_sgpr_count 2
		.amdhsa_user_sgpr_dispatch_ptr 0
		.amdhsa_user_sgpr_queue_ptr 0
		.amdhsa_user_sgpr_kernarg_segment_ptr 1
		.amdhsa_user_sgpr_dispatch_id 0
		.amdhsa_user_sgpr_kernarg_preload_length 0
		.amdhsa_user_sgpr_kernarg_preload_offset 0
		.amdhsa_user_sgpr_private_segment_size 0
		.amdhsa_uses_dynamic_stack 0
		.amdhsa_enable_private_segment 0
		.amdhsa_system_sgpr_workgroup_id_x 1
		.amdhsa_system_sgpr_workgroup_id_y 0
		.amdhsa_system_sgpr_workgroup_id_z 0
		.amdhsa_system_sgpr_workgroup_info 0
		.amdhsa_system_vgpr_workitem_id 2
		.amdhsa_next_free_vgpr 256
		.amdhsa_next_free_sgpr 102
		.amdhsa_accum_offset 256
		.amdhsa_reserve_vcc 1
		.amdhsa_float_round_mode_32 0
		.amdhsa_float_round_mode_16_64 0
		.amdhsa_float_denorm_mode_32 3
		.amdhsa_float_denorm_mode_16_64 3
		.amdhsa_dx10_clamp 1
		.amdhsa_ieee_mode 1
		.amdhsa_fp16_overflow 0
		.amdhsa_tg_split 0
		.amdhsa_exception_fp_ieee_invalid_op 0
		.amdhsa_exception_fp_denorm_src 0
		.amdhsa_exception_fp_ieee_div_zero 0
		.amdhsa_exception_fp_ieee_overflow 0
		.amdhsa_exception_fp_ieee_underflow 0
		.amdhsa_exception_fp_ieee_inexact 0
		.amdhsa_exception_int_div_zero 0
	.end_amdhsa_kernel

amdhsa.kernels:
  - .agpr_count:     0
    .args:
      - .offset:         0
        .size:           200
        .value_kind:     by_value
      - .offset:         200
        .size:           4
        .value_kind:     hidden_block_count_x
      - .offset:         204
        .size:           4
        .value_kind:     hidden_block_count_y
      - .offset:         208
        .size:           4
        .value_kind:     hidden_block_count_z
      - .offset:         212
        .size:           2
        .value_kind:     hidden_group_size_x
      - .offset:         214
        .size:           2
        .value_kind:     hidden_group_size_y
      - .offset:         216
        .size:           2
        .value_kind:     hidden_group_size_z
      - .offset:         218
        .size:           2
        .value_kind:     hidden_remainder_x
      - .offset:         220
        .size:           2
        .value_kind:     hidden_remainder_y
      - .offset:         222
        .size:           2
        .value_kind:     hidden_remainder_z
      - .offset:         240
        .size:           8
        .value_kind:     hidden_global_offset_x
      - .offset:         248
        .size:           8
        .value_kind:     hidden_global_offset_y
      - .offset:         256
        .size:           8
        .value_kind:     hidden_global_offset_z
      - .offset:         264
        .size:           2
        .value_kind:     hidden_grid_dims
      - .offset:         288
        .size:           8
        .value_kind:     hidden_multigrid_sync_arg
      - .offset:         320
        .size:           4
        .value_kind:     hidden_dynamic_lds_size
    .group_segment_fixed_size: 0
    .kernarg_segment_align: 8
    .kernarg_segment_size: 456
    .language:       OpenCL C
    .language_version:
      - 2
      - 0
    .max_flat_workgroup_size: 512
    .name:           _Z8mega_fwd4Args
    .private_segment_fixed_size: 0
    .sgpr_count:     108
    .sgpr_spill_count: 173
    .symbol:         _Z8mega_fwd4Args.kd
    .uniform_work_group_size: 1
    .uses_dynamic_stack: false
    .vgpr_count:     256
    .vgpr_spill_count: 0
    .wavefront_size: 64
